# staging wave: five array base pairs held in SGPRs, one VGPR offset add per group replaces ten dependent scalar adds before the loads
# speedup vs baseline: 1.0303x; 1.0054x over previous
; #define LAS3 __attribute__((address_space(3)))
; DEV void rwkv_helper(const Params& p, const Ctx& cx, int l, int unit, int lane, char* ring) {
;   const int d = unit & 1, h = (unit >> 1) & 15, b = unit >> 5;
;   const int j = lane >> 4, s = lane & 15;
;   const h16* SC = (const h16*)(p.ws + OFF_SCAN);
;   const char* pR = (const char*)(SC + 0 * ARR + h * 64);
;   const char* pK = (const char*)(SC + 1 * ARR + h * 64);
;   const char* pV = (const char*)(SC + 2 * ARR + h * 64);
;   const char* pKK = (const char*)(SC + 3 * ARR + h * 64);
;   const char* pA = (const char*)(SC + (size_t)(4 + d) * ARR + h * 64);
;   const char* pW = (const char*)(SC + (size_t)(6 + d) * ARR + h * 64);
;   const int jm = d ? 3 - j : j;
;   const unsigned vo0 = (unsigned)(jm * 2048 + s * 8);
;   f4v ka4, om4;
;   {
;     float4 t = *(const float4*)(p.rwkv_k_a + (size_t)l * 1024 + h * 64 + 4 * s);
;     ka4 = f4v{t.x, t.y, t.z, t.w};
;     om4 = 1.f - ka4;
;   }
;   struct RGH { u2v w, a, kk, k, r, v; };
;   RGH q0, q1, q2, q3, q4, q5, q6, q7;
;   const unsigned wofs = (unsigned)(j * 128 + s * 8);
;   const unsigned vwofs = (unsigned)(2560 + j * 128 + s * 8);
;   LAS3 volatile int* pflag = (LAS3 volatile int*)(ring + RW_FLAGS);
;   LAS3 volatile int* cflag = (LAS3 volatile int*)(ring + RW_FLAGS + 64);
;   int cmin = 0;
;     ...
;   RH_LOAD(q0, 0); RH_LOAD(q1, 1); RH_LOAD(q2, 2); RH_LOAD(q3, 3); RH_LOAD(q4, 4); RH_LOAD(q5, 5); RH_LOAD(q6, 6); RH_LOAD(q7, 7);
; DEV void phase_scan(const Params& p, const Ctx& cx, int l, char* smem) {
;     ...
;     __syncthreads();
;     if (wid == 4 && lane < 8) *(LAS3 volatile int*)(smem + RW_FLAGS + (lane == 0 ? 0 : 64 + (lane & 3) * 4)) = 0;
;     __syncthreads();
;     const int unit = slot & 63;
;     ...
;     if (wid < 4) { __builtin_amdgcn_s_setprio(3); rwkv_consumer(p, cx, l, (unit << 4) | ((slot >> 6) << 2) | wid, lane, smem, wid); __builtin_amdgcn_s_setprio(0); }
;     else if (wid == 4) { __builtin_amdgcn_s_setprio(1); rwkv_helper(p, cx, l, unit, lane, smem); __builtin_amdgcn_s_setprio(0); }
.LBB0_177:
	s_waitcnt lgkmcnt(0)
	s_barrier
	s_and_saveexec_b64 s[42:43], s[70:71]
	ds_write_b32 v118, v129 offset:49152
	s_or_b64 exec, exec, s[42:43]
	s_and_b32 s34, s31, 63
	s_and_b64 vcc, exec, s[72:73]
	s_waitcnt lgkmcnt(0)
	s_barrier
	s_cbranch_vccz .LBB0_223
	s_mov_b64 s[88:89], 0
	s_and_b64 vcc, exec, s[68:69]
	s_mov_b64 s[42:43], 0
	s_cbranch_vccz .LBB0_224
	s_setprio 1
	v_lshl_add_u32 v183, v116, 1, v116
	v_mul_u32_u24_e32 v182, 0x7e, v107
	v_sub_u32_e32 v182, v183, v182
	v_and_b32_e32 v186, 1, v107
	v_mul_u32_u24_e32 v186, 0x78, v186
	v_sub_u32_e32 v186, v116, v186
	s_lshl_b32 s0, s34, 5
	s_and_b32 s5, s0, 0x3c0
	s_and_b32 s23, s31, 1
	s_bfe_i32 s4, s31, 0x10000
	s_lshr_b32 s22, s34, 5
	s_lshl_b32 s10, s5, 1
	s_add_u32 s94, s2, s10
	s_addc_u32 s95, s3, 0
	v_readlane_b32 s0, v241, 30
	v_readlane_b32 s1, v241, 31
	s_add_u32 s97, s0, s10
	s_addc_u32 s99, s1, 0
	v_readlane_b32 s0, v241, 32
	v_readlane_b32 s1, v241, 33
	s_add_u32 s0, s0, s10
	s_addc_u32 s1, s1, 0
	v_readlane_b32 s36, v241, 42
	v_readlane_b32 s37, v241, 43
	s_add_u32 s8, s36, s10
	s_addc_u32 s84, s37, 0
	s_mul_i32 s33, s23, 0x4100000
	s_add_u32 s33, s2, s33
	s_addc_u32 s35, s3, 0
	s_add_u32 s10, s33, s10
	s_addc_u32 s33, s35, 0
	s_add_u32 s85, s10, 0x10400000
	s_addc_u32 s86, s33, 0
	s_add_u32 s87, s10, 0x18600000
	s_addc_u32 s35, s33, 0
	s_lshl_b32 s33, s22, 8
	s_bitset1_b32 s33, 15
	s_and_b32 s4, s4, 0xfc
	s_or_b32 s4, s33, s4
	s_lshl_b32 s10, s5, 2
	s_lshl_b32 s42, s4, 11
	s_add_u32 s4, s87, s42
	s_addc_u32 s5, s35, 0
	s_add_u32 s36, s85, s42
	s_addc_u32 s37, s86, 0
	s_add_u32 s44, s8, s42
	s_addc_u32 s45, s84, 0
	s_add_u32 s90, s97, s42
	s_addc_u32 s91, s99, 0
	s_add_u32 s92, s94, s42
	s_addc_u32 s93, s95, 0
	s_add_u32 vcc_lo, s0, s42
	s_addc_u32 vcc_hi, s1, 0
	s_cmp_eq_u32 s23, 0
	s_cselect_b64 s[42:43], -1, 0
	v_cndmask_b32_e64 v0, v109, v108, s[42:43]
	v_or_b32_e32 v119, v0, v110
	v_lshl_add_u64 v[0:1], v[80:81], 0, s[10:11]
	s_waitcnt vmcnt(0)
	v_mov_b32_e32 v8, v119
	global_load_dwordx4 v[0:3], v[0:1], off
	global_load_dwordx2 v[4:5], v8, s[4:5]
	global_load_dwordx2 v[36:37], v8, s[36:37]
	global_load_dwordx2 v[6:7], v8, s[44:45]
	global_load_dwordx2 v[44:45], v8, s[90:91]
	global_load_dwordx2 v[38:39], v8, s[92:93]
	s_and_b64 s[4:5], s[42:43], exec
	s_cselect_b32 s4, 4, 0xf8
	s_cselect_b32 s37, 8, 0xf4
	s_cselect_b32 s44, 12, 0xf0
	s_cselect_b32 s45, 16, 0xec
	s_cselect_b32 s36, 20, 0xe8
	s_cselect_b32 s23, 24, 0xe4
	s_cselect_b32 s10, 28, 0xe0
	s_or_b32 s4, s33, s4
	s_lshl_b32 s90, s4, 11
	s_add_u32 s4, s87, s90
	v_mov_b32_e32 v12, v119
	s_addc_u32 s5, s35, 0
	global_load_dwordx2 v[8:9], v12, s[4:5]
	s_add_u32 s4, s85, s90
	s_addc_u32 s5, s86, 0
	global_load_dwordx2 v[40:41], v12, s[4:5]
	s_add_u32 s4, s8, s90
	s_addc_u32 s5, s84, 0
	global_load_dwordx2 v[10:11], v12, s[4:5]
	s_add_u32 s4, s97, s90
	s_addc_u32 s5, s99, 0
	global_load_dwordx2 v[52:53], v12, s[4:5]
	s_add_u32 s4, s94, s90
	s_addc_u32 s5, s95, 0
	global_load_dwordx2 v[46:47], v12, s[4:5]
	s_add_u32 s4, s0, s90
	s_addc_u32 s5, s1, 0
	s_or_b32 s4, s33, s37
	s_lshl_b32 s37, s4, 11
	s_add_u32 s4, s87, s37
	v_mov_b32_e32 v16, v119
	s_addc_u32 s5, s35, 0
	global_load_dwordx2 v[12:13], v16, s[4:5]
	s_add_u32 s4, s85, s37
	s_addc_u32 s5, s86, 0
	global_load_dwordx2 v[48:49], v16, s[4:5]
	s_add_u32 s4, s8, s37
	s_addc_u32 s5, s84, 0
	global_load_dwordx2 v[14:15], v16, s[4:5]
	s_add_u32 s4, s97, s37
	s_addc_u32 s5, s99, 0
	global_load_dwordx2 v[60:61], v16, s[4:5]
	s_add_u32 s4, s94, s37
	s_addc_u32 s5, s95, 0
	global_load_dwordx2 v[54:55], v16, s[4:5]
	s_add_u32 s4, s0, s37
	s_addc_u32 s5, s1, 0
	s_or_b32 s4, s33, s44
	s_lshl_b32 s37, s4, 11
	s_add_u32 s4, s87, s37
	v_mov_b32_e32 v20, v119
	s_addc_u32 s5, s35, 0
	global_load_dwordx2 v[16:17], v20, s[4:5]
	s_add_u32 s4, s85, s37
	s_addc_u32 s5, s86, 0
	global_load_dwordx2 v[56:57], v20, s[4:5]
	s_add_u32 s4, s8, s37
	s_addc_u32 s5, s84, 0
	global_load_dwordx2 v[18:19], v20, s[4:5]
	s_add_u32 s4, s97, s37
	s_addc_u32 s5, s99, 0
	global_load_dwordx2 v[66:67], v20, s[4:5]
	s_add_u32 s4, s94, s37
	s_addc_u32 s5, s95, 0
	global_load_dwordx2 v[62:63], v20, s[4:5]
	s_add_u32 s4, s0, s37
	s_addc_u32 s5, s1, 0
	s_or_b32 s4, s33, s45
	s_lshl_b32 s37, s4, 11
	s_add_u32 s4, s87, s37
	v_mov_b32_e32 v24, v119
	s_addc_u32 s5, s35, 0
	global_load_dwordx2 v[20:21], v24, s[4:5]
	s_add_u32 s4, s85, s37
	s_addc_u32 s5, s86, 0
	global_load_dwordx2 v[64:65], v24, s[4:5]
	s_add_u32 s4, s8, s37
	s_addc_u32 s5, s84, 0
	global_load_dwordx2 v[22:23], v24, s[4:5]
	s_add_u32 s4, s97, s37
	s_addc_u32 s5, s99, 0
	global_load_dwordx2 v[76:77], v24, s[4:5]
	s_add_u32 s4, s94, s37
	s_addc_u32 s5, s95, 0
	global_load_dwordx2 v[70:71], v24, s[4:5]
	s_add_u32 s4, s0, s37
	s_addc_u32 s5, s1, 0
	s_or_b32 s4, s33, s36
	s_lshl_b32 s36, s4, 11
	s_add_u32 s4, s87, s36
	v_mov_b32_e32 v28, v119
	s_addc_u32 s5, s35, 0
	global_load_dwordx2 v[24:25], v28, s[4:5]
	s_add_u32 s4, s85, s36
	s_addc_u32 s5, s86, 0
	global_load_dwordx2 v[72:73], v28, s[4:5]
	s_add_u32 s4, s8, s36
	s_addc_u32 s5, s84, 0
	global_load_dwordx2 v[26:27], v28, s[4:5]
	s_add_u32 s4, s97, s36
	s_addc_u32 s5, s99, 0
	global_load_dwordx2 v[84:85], v28, s[4:5]
	s_add_u32 s4, s94, s36
	s_addc_u32 s5, s95, 0
	global_load_dwordx2 v[78:79], v28, s[4:5]
	s_add_u32 s4, s0, s36
	s_addc_u32 s5, s1, 0
	s_or_b32 s4, s33, s23
	s_lshl_b32 s23, s4, 11
	s_add_u32 s4, s87, s23
	v_mov_b32_e32 v32, v119
	s_addc_u32 s5, s35, 0
	global_load_dwordx2 v[28:29], v32, s[4:5]
	s_add_u32 s4, s85, s23
	s_addc_u32 s5, s86, 0
	global_load_dwordx2 v[82:83], v32, s[4:5]
	s_add_u32 s4, s8, s23
	s_addc_u32 s5, s84, 0
	global_load_dwordx2 v[30:31], v32, s[4:5]
	s_add_u32 s4, s97, s23
	s_addc_u32 s5, s99, 0
	global_load_dwordx2 v[98:99], v32, s[4:5]
	s_add_u32 s4, s94, s23
	s_addc_u32 s5, s95, 0
	global_load_dwordx2 v[88:89], v32, s[4:5]
	s_add_u32 s4, s0, s23
	s_addc_u32 s5, s1, 0
	s_or_b32 s4, s33, s10
	s_lshl_b32 s10, s4, 11
	s_add_u32 s4, s87, s10
	v_mov_b32_e32 v92, v119
	s_addc_u32 s5, s35, 0
	global_load_dwordx2 v[32:33], v92, s[4:5]
	s_add_u32 s4, s85, s10
	s_addc_u32 s5, s86, 0
	global_load_dwordx2 v[90:91], v92, s[4:5]
	s_add_u32 s4, s8, s10
	s_addc_u32 s5, s84, 0
	global_load_dwordx2 v[34:35], v92, s[4:5]
	s_add_u32 s4, s97, s10
	s_addc_u32 s5, s99, 0
	global_load_dwordx2 v[102:103], v92, s[4:5]
	s_add_u32 s4, s94, s10
	s_addc_u32 s5, s95, 0
	global_load_dwordx2 v[100:101], v92, s[4:5]
	s_add_u32 s4, s0, s10
	s_addc_u32 s5, s1, 0
	s_mov_b32 s36, 0
	s_waitcnt vmcnt(40)
	v_sub_f32_e32 v93, 1.0, v3
	v_sub_f32_e32 v92, 1.0, v2
	v_sub_f32_e32 v95, 1.0, v1
	v_sub_f32_e32 v94, 1.0, v0
	s_lshl_b32 s10, s22, 14
	s_mov_b32 s37, 0
	s_mov_b32 s74, s87
	s_mov_b32 s75, s35
	s_mov_b32 s76, s85
	s_mov_b32 s77, s86
	s_mov_b32 s78, s8
	s_mov_b32 s79, s84
	s_mov_b32 s80, s97
	s_mov_b32 s81, s99
	s_mov_b32 s82, s94
	s_mov_b32 s83, s95
	s_branch .LBB0_183
.LBB0_182:
	s_min_u32 s4, s37, 0x1030
	s_lshl_b32 s4, s4, 2
	s_cmp_gt_u32 s37, 48
	s_cselect_b32 s5, 0xffffff3c, 60
	s_cselect_b32 s23, s10, s33
	s_cselect_b32 s37, s46, 0xfc
	s_add_i32 s44, s4, s5
	s_sub_i32 s37, s37, s44
	s_waitcnt vmcnt(38)
	v_cvt_f32_f16_sdwa v123, v90 dst_sel:DWORD dst_unused:UNUSED_PAD src0_sel:WORD_1
	v_cvt_f32_f16_sdwa v125, v91 dst_sel:DWORD dst_unused:UNUSED_PAD src0_sel:WORD_1
	v_cvt_f32_f16_e32 v122, v90
	v_cvt_f32_f16_e32 v124, v91
	s_and_b64 s[4:5], s[42:43], exec
	s_waitcnt vmcnt(36)
	v_cvt_f32_f16_sdwa v127, v102 dst_sel:DWORD dst_unused:UNUSED_PAD src0_sel:WORD_1
	v_cvt_f32_f16_sdwa v133, v103 dst_sel:DWORD dst_unused:UNUSED_PAD src0_sel:WORD_1
	v_cvt_f32_f16_e32 v126, v102
	v_cvt_f32_f16_e32 v132, v103
	s_cselect_b32 s4, s44, s37
	s_add_i32 s4, s4, s23
	s_ashr_i32 s5, s4, 31
	v_pk_fma_f32 v[102:103], v[2:3], v[124:125], v[92:93]
	v_pk_fma_f32 v[122:123], v[0:1], v[122:123], v[94:95]
	s_lshl_b64 s[4:5], s[4:5], 11
	v_add_u32_e32 v187, s4, v119
	v_pk_mul_f32 v[102:103], v[102:103], v[132:133]
	v_pk_mul_f32 v[126:127], v[122:123], v[126:127]
	v_pk_mul_f16 v123, v91, v35
	v_pk_mul_f16 v122, v90, v34
	v_cvt_pk_f16_f32 v125, v102, v103
	v_cvt_pk_f16_f32 v124, v126, v127
	ds_write_b128 v120, v[32:35] offset:21504
	ds_write_b128 v120, v[122:125] offset:22528
	s_waitcnt vmcnt(35)
	v_add_u32_e32 v185, v121, v186
	ds_write_b64 v185, v[100:101] offset:23552
	v_mov_b32_e32 v32, s22
	s_waitcnt lgkmcnt(0)
	ds_write_b32 v161, v32 offset:49152
	global_load_dwordx2 v[32:33], v187, s[74:75]
	global_load_dwordx2 v[90:91], v187, s[76:77]
	global_load_dwordx2 v[34:35], v187, s[78:79]
	global_load_dwordx2 v[102:103], v187, s[80:81]
	global_load_dwordx2 v[100:101], v187, s[82:83]
	s_nop 0
	s_andn2_b64 vcc, exec, s[90:91]
	s_mov_b32 s37, s22
	s_cbranch_vccz .LBB0_242

.LBB0_185:
	s_waitcnt vmcnt(38)
	v_cvt_f32_f16_sdwa v121, v36 dst_sel:DWORD dst_unused:UNUSED_PAD src0_sel:WORD_1
	v_cvt_f32_f16_e32 v120, v36
	s_waitcnt vmcnt(36)
	v_cvt_f32_f16_sdwa v125, v44 dst_sel:DWORD dst_unused:UNUSED_PAD src0_sel:WORD_1
	v_cvt_f32_f16_e32 v124, v44
	s_and_b32 s4, s37, 8
	v_cvt_f32_f16_sdwa v123, v37 dst_sel:DWORD dst_unused:UNUSED_PAD src0_sel:WORD_1
	v_cvt_f32_f16_e32 v122, v37
	s_mulk_i32 s4, 0xc00
	s_add_i32 s4, s4, 16
	v_pk_fma_f32 v[120:121], v[0:1], v[120:121], v[94:95]
	s_or_b32 s23, s37, 1
	s_add_i32 s22, s37, 8
	v_pk_mul_f32 v[120:121], v[120:121], v[124:125]
	s_cmpk_gt_u32 s37, 0x1037
	v_cvt_f32_f16_sdwa v127, v45 dst_sel:DWORD dst_unused:UNUSED_PAD src0_sel:WORD_1
	v_cvt_f32_f16_e32 v126, v45
	v_pk_fma_f32 v[44:45], v[2:3], v[122:123], v[92:93]
	v_pk_mul_f16 v122, v36, v6
	v_cvt_pk_f16_f32 v124, v120, v121
	v_add_u32_e32 v36, s4, v113
	v_add_u32_e32 v121, s4, v111
	s_cselect_b64 s[90:91], -1, 0
	s_lshl_b32 s4, s22, 2
	s_cmpk_lt_u32 s37, 0x1038
	s_cselect_b32 s4, s4, 0x40fc
	s_add_i32 s5, s4, 0xffffff00
	s_min_u32 s44, s5, s4
	s_cmpk_gt_u32 s4, 0xff
	s_movk_i32 s4, 0x3fff
	s_cselect_b32 s4, s4, 0xff
	s_cselect_b32 s45, s10, s33
	s_sub_i32 s4, s4, s44
	s_add_i32 vcc_lo, s4, -3
	s_and_b64 s[4:5], s[42:43], exec
	s_cselect_b32 s4, s44, vcc_lo
	s_add_i32 s4, s4, s45
	s_ashr_i32 s5, s4, 31
	s_lshl_b64 s[4:5], s[4:5], 11
	v_add_u32_e32 v187, s4, v119
	v_pk_mul_f32 v[44:45], v[44:45], v[126:127]
	v_add_u32_e32 v120, v36, v128
	v_pk_mul_f16 v123, v37, v7
	v_cvt_pk_f16_f32 v125, v44, v45
	ds_write_b128 v120, v[4:7]
	ds_write_b128 v120, v[122:125] offset:1024
	s_waitcnt vmcnt(35)
	v_add_u32_e32 v185, v121, v186
	ds_write_b64 v185, v[38:39] offset:2048
	v_mov_b32_e32 v4, s23
	s_waitcnt lgkmcnt(0)
	ds_write_b32 v161, v4 offset:49152
	global_load_dwordx2 v[4:5], v187, s[74:75]
	global_load_dwordx2 v[36:37], v187, s[76:77]
	global_load_dwordx2 v[6:7], v187, s[78:79]
	global_load_dwordx2 v[44:45], v187, s[80:81]
	global_load_dwordx2 v[38:39], v187, s[82:83]
	s_nop 0
	v_cndmask_b32_e64 v122, 0, 1, s[92:93]
	v_cmp_ne_u32_e64 s[44:45], 1, v122
	s_andn2_b64 vcc, exec, s[92:93]
	s_cbranch_vccnz .LBB0_187
	s_add_i32 s4, s37, -14
	s_cmp_ge_i32 s36, s4
	s_cbranch_scc0 .LBB0_203
.LBB0_187:
	s_waitcnt vmcnt(38)
	v_cvt_f32_f16_sdwa v123, v40 dst_sel:DWORD dst_unused:UNUSED_PAD src0_sel:WORD_1
	v_cvt_f32_f16_sdwa v125, v41 dst_sel:DWORD dst_unused:UNUSED_PAD src0_sel:WORD_1
	v_cvt_f32_f16_e32 v122, v40
	v_cvt_f32_f16_e32 v124, v41
	s_waitcnt vmcnt(36)
	v_cvt_f32_f16_sdwa v127, v52 dst_sel:DWORD dst_unused:UNUSED_PAD src0_sel:WORD_1
	v_cvt_f32_f16_sdwa v133, v53 dst_sel:DWORD dst_unused:UNUSED_PAD src0_sel:WORD_1
	v_cvt_f32_f16_e32 v126, v52
	v_cvt_f32_f16_e32 v132, v53
	s_and_b32 s4, s23, 9
	s_mulk_i32 s4, 0xc00
	s_add_i32 s4, s4, 16
	v_pk_fma_f32 v[52:53], v[2:3], v[124:125], v[92:93]
	v_pk_fma_f32 v[122:123], v[0:1], v[122:123], v[94:95]
	v_pk_mul_f32 v[52:53], v[52:53], v[132:133]
	v_pk_mul_f32 v[126:127], v[122:123], v[126:127]
	v_pk_mul_f16 v122, v40, v10
	v_add3_u32 v40, s4, v113, v128
	v_pk_mul_f16 v123, v41, v11
	v_cvt_pk_f16_f32 v125, v52, v53
	v_cvt_pk_f16_f32 v124, v126, v127
	ds_write_b128 v40, v[8:11]
	ds_write_b128 v40, v[122:125] offset:1024
	v_add_u32_e32 v8, s4, v111
	s_or_b32 s4, s37, 2
	s_waitcnt vmcnt(35)
	v_add_u32_e32 v185, v8, v186
	ds_write_b64 v185, v[46:47] offset:2048
	v_mov_b32_e32 v8, s4
	s_min_u32 s4, s37, 0x1036
	s_lshl_b32 s4, s4, 2
	s_cmp_gt_u32 s37, 54
	s_cselect_b32 s5, 0xffffff24, 36
	s_cselect_b32 s23, s10, s33
	s_cselect_b32 s92, s46, 0xfc
	s_add_i32 s93, s4, s5
	s_sub_i32 s92, s92, s93
	s_and_b64 s[4:5], s[42:43], exec
	s_cselect_b32 s4, s93, s92
	s_add_i32 s4, s4, s23
	s_ashr_i32 s5, s4, 31
	s_lshl_b64 s[4:5], s[4:5], 11
	v_add_u32_e32 v187, s4, v119
	s_waitcnt lgkmcnt(0)
	ds_write_b32 v161, v8 offset:49152
	global_load_dwordx2 v[8:9], v187, s[74:75]
	global_load_dwordx2 v[40:41], v187, s[76:77]
	global_load_dwordx2 v[10:11], v187, s[78:79]
	global_load_dwordx2 v[52:53], v187, s[80:81]
	global_load_dwordx2 v[46:47], v187, s[82:83]
	s_nop 0
	s_and_b64 vcc, exec, s[44:45]
	s_cbranch_vccnz .LBB0_189
	s_add_i32 s4, s37, -13
	s_cmp_ge_i32 s36, s4
	s_cbranch_scc0 .LBB0_206
.LBB0_189:
	s_waitcnt vmcnt(38)
	v_cvt_f32_f16_sdwa v123, v48 dst_sel:DWORD dst_unused:UNUSED_PAD src0_sel:WORD_1
	v_cvt_f32_f16_sdwa v125, v49 dst_sel:DWORD dst_unused:UNUSED_PAD src0_sel:WORD_1
	v_cvt_f32_f16_e32 v122, v48
	v_cvt_f32_f16_e32 v124, v49
	s_waitcnt vmcnt(36)
	v_cvt_f32_f16_sdwa v127, v60 dst_sel:DWORD dst_unused:UNUSED_PAD src0_sel:WORD_1
	v_cvt_f32_f16_sdwa v133, v61 dst_sel:DWORD dst_unused:UNUSED_PAD src0_sel:WORD_1
	v_cvt_f32_f16_e32 v126, v60
	v_cvt_f32_f16_e32 v132, v61
	v_pk_fma_f32 v[60:61], v[2:3], v[124:125], v[92:93]
	v_pk_fma_f32 v[122:123], v[0:1], v[122:123], v[94:95]
	s_or_b32 s4, s37, 3
	v_pk_mul_f32 v[60:61], v[60:61], v[132:133]
	v_pk_mul_f32 v[126:127], v[122:123], v[126:127]
	v_pk_mul_f16 v123, v49, v15
	v_pk_mul_f16 v122, v48, v14
	v_cvt_pk_f16_f32 v125, v60, v61
	v_cvt_pk_f16_f32 v124, v126, v127
	ds_write_b128 v120, v[12:15] offset:6144
	ds_write_b128 v120, v[122:125] offset:7168
	s_waitcnt vmcnt(35)
	v_add_u32_e32 v185, v121, v186
	ds_write_b64 v185, v[54:55] offset:8192
	v_mov_b32_e32 v12, s4
	s_min_u32 s4, s37, 0x1035
	s_lshl_b32 s4, s4, 2
	s_cmp_gt_u32 s37, 53
	s_cselect_b32 s5, 0xffffff28, 40
	s_cselect_b32 s23, s10, s33
	s_cselect_b32 s92, s46, 0xfc
	s_add_i32 s93, s4, s5
	s_sub_i32 s92, s92, s93
	s_and_b64 s[4:5], s[42:43], exec
	s_cselect_b32 s4, s93, s92
	s_add_i32 s4, s4, s23
	s_ashr_i32 s5, s4, 31
	s_lshl_b64 s[4:5], s[4:5], 11
	v_add_u32_e32 v187, s4, v119
	s_waitcnt lgkmcnt(0)
	ds_write_b32 v161, v12 offset:49152
	global_load_dwordx2 v[12:13], v187, s[74:75]
	global_load_dwordx2 v[48:49], v187, s[76:77]
	global_load_dwordx2 v[14:15], v187, s[78:79]
	global_load_dwordx2 v[60:61], v187, s[80:81]
	global_load_dwordx2 v[54:55], v187, s[82:83]
	s_nop 0
	s_and_b64 vcc, exec, s[44:45]
	s_cbranch_vccnz .LBB0_191
	s_add_i32 s4, s37, -12
	s_cmp_ge_i32 s36, s4
	s_cbranch_scc0 .LBB0_209
.LBB0_191:
	s_waitcnt vmcnt(38)
	v_cvt_f32_f16_sdwa v123, v56 dst_sel:DWORD dst_unused:UNUSED_PAD src0_sel:WORD_1
	v_cvt_f32_f16_sdwa v125, v57 dst_sel:DWORD dst_unused:UNUSED_PAD src0_sel:WORD_1
	v_cvt_f32_f16_e32 v122, v56
	v_cvt_f32_f16_e32 v124, v57
	s_waitcnt vmcnt(36)
	v_cvt_f32_f16_sdwa v127, v66 dst_sel:DWORD dst_unused:UNUSED_PAD src0_sel:WORD_1
	v_cvt_f32_f16_sdwa v133, v67 dst_sel:DWORD dst_unused:UNUSED_PAD src0_sel:WORD_1
	v_cvt_f32_f16_e32 v126, v66
	v_cvt_f32_f16_e32 v132, v67
	v_pk_fma_f32 v[66:67], v[2:3], v[124:125], v[92:93]
	v_pk_fma_f32 v[122:123], v[0:1], v[122:123], v[94:95]
	s_or_b32 s4, s37, 4
	v_pk_mul_f32 v[66:67], v[66:67], v[132:133]
	v_pk_mul_f32 v[126:127], v[122:123], v[126:127]
	v_pk_mul_f16 v123, v57, v19
	v_pk_mul_f16 v122, v56, v18
	v_cvt_pk_f16_f32 v125, v66, v67
	v_cvt_pk_f16_f32 v124, v126, v127
	ds_write_b128 v120, v[16:19] offset:9216
	ds_write_b128 v120, v[122:125] offset:10240
	s_waitcnt vmcnt(35)
	v_add_u32_e32 v185, v121, v186
	ds_write_b64 v185, v[62:63] offset:11264
	v_mov_b32_e32 v16, s4
	s_min_u32 s4, s37, 0x1034
	s_lshl_b32 s4, s4, 2
	s_cmp_gt_u32 s37, 52
	s_cselect_b32 s5, 0xffffff2c, 44
	s_cselect_b32 s23, s10, s33
	s_cselect_b32 s92, s46, 0xfc
	s_add_i32 s93, s4, s5
	s_sub_i32 s92, s92, s93
	s_and_b64 s[4:5], s[42:43], exec
	s_cselect_b32 s4, s93, s92
	s_add_i32 s4, s4, s23
	s_ashr_i32 s5, s4, 31
	s_lshl_b64 s[4:5], s[4:5], 11
	v_add_u32_e32 v187, s4, v119
	s_waitcnt lgkmcnt(0)
	ds_write_b32 v161, v16 offset:49152
	global_load_dwordx2 v[16:17], v187, s[74:75]
	global_load_dwordx2 v[56:57], v187, s[76:77]
	global_load_dwordx2 v[18:19], v187, s[78:79]
	global_load_dwordx2 v[66:67], v187, s[80:81]
	global_load_dwordx2 v[62:63], v187, s[82:83]
	s_nop 0
	s_and_b64 vcc, exec, s[44:45]
	s_cbranch_vccnz .LBB0_193
	s_add_i32 s4, s37, -11
	s_cmp_ge_i32 s36, s4
	s_cbranch_scc0 .LBB0_212
.LBB0_193:
	s_waitcnt vmcnt(38)
	v_cvt_f32_f16_sdwa v123, v64 dst_sel:DWORD dst_unused:UNUSED_PAD src0_sel:WORD_1
	v_cvt_f32_f16_sdwa v125, v65 dst_sel:DWORD dst_unused:UNUSED_PAD src0_sel:WORD_1
	v_cvt_f32_f16_e32 v122, v64
	v_cvt_f32_f16_e32 v124, v65
	s_waitcnt vmcnt(36)
	v_cvt_f32_f16_sdwa v127, v76 dst_sel:DWORD dst_unused:UNUSED_PAD src0_sel:WORD_1
	v_cvt_f32_f16_sdwa v133, v77 dst_sel:DWORD dst_unused:UNUSED_PAD src0_sel:WORD_1
	v_cvt_f32_f16_e32 v126, v76
	v_cvt_f32_f16_e32 v132, v77
	v_pk_fma_f32 v[76:77], v[2:3], v[124:125], v[92:93]
	v_pk_fma_f32 v[122:123], v[0:1], v[122:123], v[94:95]
	s_or_b32 s4, s37, 5
	v_pk_mul_f32 v[76:77], v[76:77], v[132:133]
	v_pk_mul_f32 v[126:127], v[122:123], v[126:127]
	v_pk_mul_f16 v123, v65, v23
	v_pk_mul_f16 v122, v64, v22
	v_cvt_pk_f16_f32 v125, v76, v77
	v_cvt_pk_f16_f32 v124, v126, v127
	ds_write_b128 v120, v[20:23] offset:12288
	ds_write_b128 v120, v[122:125] offset:13312
	s_waitcnt vmcnt(35)
	v_add_u32_e32 v185, v121, v186
	ds_write_b64 v185, v[70:71] offset:14336
	v_mov_b32_e32 v20, s4
	s_min_u32 s4, s37, 0x1033
	s_lshl_b32 s4, s4, 2
	s_cmp_gt_u32 s37, 51
	s_cselect_b32 s5, 0xffffff30, 48
	s_cselect_b32 s23, s10, s33
	s_cselect_b32 s92, s46, 0xfc
	s_add_i32 s93, s4, s5
	s_sub_i32 s92, s92, s93
	s_and_b64 s[4:5], s[42:43], exec
	s_cselect_b32 s4, s93, s92
	s_add_i32 s4, s4, s23
	s_ashr_i32 s5, s4, 31
	s_lshl_b64 s[4:5], s[4:5], 11
	v_add_u32_e32 v187, s4, v119
	s_waitcnt lgkmcnt(0)
	ds_write_b32 v161, v20 offset:49152
	global_load_dwordx2 v[20:21], v187, s[74:75]
	global_load_dwordx2 v[64:65], v187, s[76:77]
	global_load_dwordx2 v[22:23], v187, s[78:79]
	global_load_dwordx2 v[76:77], v187, s[80:81]
	global_load_dwordx2 v[70:71], v187, s[82:83]
	s_nop 0
	s_and_b64 vcc, exec, s[44:45]
	s_cbranch_vccnz .LBB0_195
	s_add_i32 s4, s37, -10
	s_cmp_ge_i32 s36, s4
	s_cbranch_scc0 .LBB0_215
.LBB0_195:
	s_waitcnt vmcnt(38)
	v_cvt_f32_f16_sdwa v123, v72 dst_sel:DWORD dst_unused:UNUSED_PAD src0_sel:WORD_1
	v_cvt_f32_f16_sdwa v125, v73 dst_sel:DWORD dst_unused:UNUSED_PAD src0_sel:WORD_1
	v_cvt_f32_f16_e32 v122, v72
	v_cvt_f32_f16_e32 v124, v73
	s_waitcnt vmcnt(36)
	v_cvt_f32_f16_sdwa v127, v84 dst_sel:DWORD dst_unused:UNUSED_PAD src0_sel:WORD_1
	v_cvt_f32_f16_sdwa v133, v85 dst_sel:DWORD dst_unused:UNUSED_PAD src0_sel:WORD_1
	v_cvt_f32_f16_e32 v126, v84
	v_cvt_f32_f16_e32 v132, v85
	v_pk_fma_f32 v[84:85], v[2:3], v[124:125], v[92:93]
	v_pk_fma_f32 v[122:123], v[0:1], v[122:123], v[94:95]
	s_or_b32 s4, s37, 6
	v_pk_mul_f32 v[84:85], v[84:85], v[132:133]
	v_pk_mul_f32 v[126:127], v[122:123], v[126:127]
	v_pk_mul_f16 v123, v73, v27
	v_pk_mul_f16 v122, v72, v26
	v_cvt_pk_f16_f32 v125, v84, v85
	v_cvt_pk_f16_f32 v124, v126, v127
	ds_write_b128 v120, v[24:27] offset:15360
	ds_write_b128 v120, v[122:125] offset:16384
	s_waitcnt vmcnt(35)
	v_add_u32_e32 v185, v121, v186
	ds_write_b64 v185, v[78:79] offset:17408
	v_mov_b32_e32 v24, s4
	s_min_u32 s4, s37, 0x1032
	s_lshl_b32 s4, s4, 2
	s_cmp_gt_u32 s37, 50
	s_cselect_b32 s5, 0xffffff34, 52
	s_cselect_b32 s23, s10, s33
	s_cselect_b32 s92, s46, 0xfc
	s_add_i32 s93, s4, s5
	s_sub_i32 s92, s92, s93
	s_and_b64 s[4:5], s[42:43], exec
	s_cselect_b32 s4, s93, s92
	s_add_i32 s4, s4, s23
	s_ashr_i32 s5, s4, 31
	s_lshl_b64 s[4:5], s[4:5], 11
	v_add_u32_e32 v187, s4, v119
	s_waitcnt lgkmcnt(0)
	ds_write_b32 v161, v24 offset:49152
	global_load_dwordx2 v[24:25], v187, s[74:75]
	global_load_dwordx2 v[72:73], v187, s[76:77]
	global_load_dwordx2 v[26:27], v187, s[78:79]
	global_load_dwordx2 v[84:85], v187, s[80:81]
	global_load_dwordx2 v[78:79], v187, s[82:83]
	s_nop 0
	s_and_b64 vcc, exec, s[44:45]
	s_cbranch_vccnz .LBB0_197
	s_add_i32 s4, s37, -9
	s_cmp_ge_i32 s36, s4
	s_cbranch_scc0 .LBB0_218
.LBB0_197:
	s_waitcnt vmcnt(38)
	v_cvt_f32_f16_sdwa v123, v82 dst_sel:DWORD dst_unused:UNUSED_PAD src0_sel:WORD_1
	v_cvt_f32_f16_sdwa v125, v83 dst_sel:DWORD dst_unused:UNUSED_PAD src0_sel:WORD_1
	v_cvt_f32_f16_e32 v122, v82
	v_cvt_f32_f16_e32 v124, v83
	s_waitcnt vmcnt(36)
	v_cvt_f32_f16_sdwa v127, v98 dst_sel:DWORD dst_unused:UNUSED_PAD src0_sel:WORD_1
	v_cvt_f32_f16_sdwa v133, v99 dst_sel:DWORD dst_unused:UNUSED_PAD src0_sel:WORD_1
	v_cvt_f32_f16_e32 v126, v98
	v_cvt_f32_f16_e32 v132, v99
	v_pk_fma_f32 v[98:99], v[2:3], v[124:125], v[92:93]
	v_pk_fma_f32 v[122:123], v[0:1], v[122:123], v[94:95]
	s_or_b32 s4, s37, 7
	v_pk_mul_f32 v[98:99], v[98:99], v[132:133]
	v_pk_mul_f32 v[126:127], v[122:123], v[126:127]
	v_pk_mul_f16 v123, v83, v31
	v_pk_mul_f16 v122, v82, v30
	v_cvt_pk_f16_f32 v125, v98, v99
	v_cvt_pk_f16_f32 v124, v126, v127
	ds_write_b128 v120, v[28:31] offset:18432
	ds_write_b128 v120, v[122:125] offset:19456
	s_waitcnt vmcnt(35)
	v_add_u32_e32 v185, v121, v186
	ds_write_b64 v185, v[88:89] offset:20480
	v_mov_b32_e32 v28, s4
	s_min_u32 s4, s37, 0x1031
	s_lshl_b32 s4, s4, 2
	s_cmp_gt_u32 s37, 49
	s_cselect_b32 s5, 0xffffff38, 56
	s_cselect_b32 s23, s10, s33
	s_cselect_b32 s92, s46, 0xfc
	s_add_i32 s93, s4, s5
	s_sub_i32 s92, s92, s93
	s_and_b64 s[4:5], s[42:43], exec
	s_cselect_b32 s4, s93, s92
	s_add_i32 s4, s4, s23
	s_ashr_i32 s5, s4, 31
	s_lshl_b64 s[4:5], s[4:5], 11
	v_add_u32_e32 v187, s4, v119
	s_waitcnt lgkmcnt(0)
	ds_write_b32 v161, v28 offset:49152
	global_load_dwordx2 v[28:29], v187, s[74:75]
	global_load_dwordx2 v[82:83], v187, s[76:77]
	global_load_dwordx2 v[30:31], v187, s[78:79]
	global_load_dwordx2 v[98:99], v187, s[80:81]
	global_load_dwordx2 v[88:89], v187, s[82:83]
	s_nop 0
	s_and_b64 vcc, exec, s[44:45]
	s_cbranch_vccnz .LBB0_182
	s_add_i32 s4, s37, -8
	s_cmp_ge_i32 s36, s4
	s_cbranch_scc0 .LBB0_221
	s_branch .LBB0_182
